# GEMM K-loops: staging (LDS writes of next tile, now unconditional, + prefetch loads) issued right behind the first MFMA block of each K-step with raised counted lgkmcnt waits; same numerics
# speedup vs baseline: 1.0602x; 1.0067x over previous
.LBB0_208:
	s_add_i32 s12, s37, -2
	s_and_b32 s12, s12, 2
	s_mul_i32 s12, s12, 0x9000
	s_add_i32 s12, s12, 0
	v_add3_u32 v200, s12, v195, v192
	ds_read_b128 v[160:163], v200
	ds_read_b128 v[168:171], v200 offset:4608
	ds_read_b128 v[172:175], v200 offset:9216
	ds_read_b128 v[176:179], v200 offset:13824
	v_add3_u32 v214, s12, v194, v192
	ds_read_b128 v[164:167], v214 offset:36864
	s_cmpk_eq_i32 s2, 0x780
	s_waitcnt lgkmcnt(0)
	v_mfma_f32_32x32x16_bf16 v[112:127], v[160:163], v[164:167], v[112:127]
	v_mfma_f32_32x32x16_bf16 v[80:95], v[168:171], v[164:167], v[80:95]
	v_mfma_f32_32x32x16_bf16 v[48:63], v[172:175], v[164:167], v[48:63]
	v_mfma_f32_32x32x16_bf16 v[16:31], v[176:179], v[164:167], v[16:31]
	ds_read_b128 v[164:167], v214 offset:41472
	s_waitcnt lgkmcnt(0)
	v_mfma_f32_32x32x16_bf16 v[96:111], v[160:163], v[164:167], v[96:111]
	v_mfma_f32_32x32x16_bf16 v[64:79], v[168:171], v[164:167], v[64:79]
	v_mfma_f32_32x32x16_bf16 v[32:47], v[172:175], v[164:167], v[32:47]
	ds_read_b128 v[160:163], v214 offset:36896
	ds_read_b128 v[168:171], v200 offset:32
	ds_read_b128 v[172:175], v200 offset:4640
	ds_read_b128 v[180:183], v200 offset:9248
	ds_read_b128 v[196:199], v200 offset:13856
	ds_read_b128 v[202:205], v214 offset:41504
	v_mfma_f32_32x32x16_bf16 v[0:15], v[176:179], v[164:167], v[0:15]
	s_and_b32 s12, s37, 2
	s_mul_i32 s12, s12, 0x9000
	v_add_u32_e32 v215, s12, v193
	s_waitcnt vmcnt(7)
	ds_write_b128 v215, v[128:131]
	s_waitcnt vmcnt(6)
	ds_write_b128 v215, v[132:135] offset:36864
	s_waitcnt vmcnt(5)
	ds_write_b128 v215, v[136:139] offset:9216
	s_waitcnt vmcnt(4)
	ds_write_b128 v215, v[140:143] offset:46080
	s_waitcnt vmcnt(3)
	ds_write_b128 v215, v[144:147] offset:18432
	s_waitcnt vmcnt(2)
	ds_write_b128 v215, v[148:151] offset:55296
	s_waitcnt vmcnt(1)
	ds_write_b128 v215, v[152:155] offset:27648
	s_waitcnt vmcnt(0)
	ds_write_b128 v215, v[156:159] offset:64512
	s_cmpk_gt_i32 s2, 0x680
	s_cbranch_scc1 .Lnl_0
	s_add_u32 s96, s92, s2
	s_addc_u32 s97, s93, s3
	s_add_u32 s98, s94, s2
	s_addc_u32 s99, s95, s3
	global_load_dwordx4 v[128:131], v248, s[96:97] offset:256
	global_load_dwordx4 v[132:135], v248, s[98:99] offset:256
	global_load_dwordx4 v[136:139], v249, s[96:97] offset:256
	global_load_dwordx4 v[140:143], v249, s[98:99] offset:256
	global_load_dwordx4 v[144:147], v250, s[96:97] offset:256
	global_load_dwordx4 v[148:151], v250, s[98:99] offset:256
	global_load_dwordx4 v[152:155], v251, s[96:97] offset:256
	global_load_dwordx4 v[156:159], v251, s[98:99] offset:256
.Lnl_0:
	s_waitcnt lgkmcnt(12)
	v_mfma_f32_32x32x16_bf16 v[112:127], v[168:171], v[160:163], v[112:127]
	s_waitcnt lgkmcnt(11)
	v_mfma_f32_32x32x16_bf16 v[80:95], v[172:175], v[160:163], v[80:95]
	s_waitcnt lgkmcnt(10)
	v_mfma_f32_32x32x16_bf16 v[48:63], v[180:183], v[160:163], v[48:63]
	s_waitcnt lgkmcnt(9)
	v_mfma_f32_32x32x16_bf16 v[16:31], v[196:199], v[160:163], v[16:31]
	s_waitcnt lgkmcnt(8)
	v_mfma_f32_32x32x16_bf16 v[96:111], v[168:171], v[202:205], v[96:111]
	v_mfma_f32_32x32x16_bf16 v[64:79], v[172:175], v[202:205], v[64:79]
	ds_read_b128 v[160:163], v214 offset:36928
	ds_read_b128 v[206:209], v214 offset:41536
	ds_read_b128 v[164:167], v200 offset:64
	ds_read_b128 v[168:171], v200 offset:4672
	ds_read_b128 v[172:175], v200 offset:9280
	ds_read_b128 v[210:213], v200 offset:13888
	v_mfma_f32_32x32x16_bf16 v[32:47], v[180:183], v[202:205], v[32:47]
	v_mfma_f32_32x32x16_bf16 v[0:15], v[196:199], v[202:205], v[0:15]
	s_waitcnt lgkmcnt(3)
	v_mfma_f32_32x32x16_bf16 v[112:127], v[164:167], v[160:163], v[112:127]
	s_waitcnt lgkmcnt(2)
	v_mfma_f32_32x32x16_bf16 v[80:95], v[168:171], v[160:163], v[80:95]
	s_waitcnt lgkmcnt(1)
	v_mfma_f32_32x32x16_bf16 v[48:63], v[172:175], v[160:163], v[48:63]
	s_waitcnt lgkmcnt(0)
	v_mfma_f32_32x32x16_bf16 v[16:31], v[210:213], v[160:163], v[16:31]
	v_mfma_f32_32x32x16_bf16 v[96:111], v[164:167], v[206:209], v[96:111]
	v_mfma_f32_32x32x16_bf16 v[64:79], v[168:171], v[206:209], v[64:79]
	v_mfma_f32_32x32x16_bf16 v[32:47], v[172:175], v[206:209], v[32:47]
	ds_read_b128 v[176:179], v214 offset:36960
	ds_read_b128 v[160:163], v214 offset:41568
	ds_read_b128 v[180:183], v200 offset:96
	ds_read_b128 v[172:175], v200 offset:4704
	ds_read_b128 v[168:171], v200 offset:9312
	ds_read_b128 v[164:167], v200 offset:13920
	v_mfma_f32_32x32x16_bf16 v[0:15], v[210:213], v[206:209], v[0:15]
	s_branch .LBB0_207

.LBB0_216:
	s_add_i32 s12, s35, -2
	s_and_b32 s12, s12, 2
	s_mul_i32 s12, s12, 0x9000
	s_add_i32 s12, s12, 0
	v_add3_u32 v214, s12, v194, v192
	ds_read_b128 v[160:163], v214 offset:36864
	v_add3_u32 v215, s12, v195, v192
	ds_read_b128 v[164:167], v215
	ds_read_b128 v[168:171], v215 offset:4608
	ds_read_b128 v[172:175], v215 offset:9216
	ds_read_b128 v[176:179], v215 offset:13824
	s_cmpk_eq_i32 s2, 0x780
	s_waitcnt lgkmcnt(3)
	v_mfma_f32_32x32x16_bf16 v[112:127], v[160:163], v[164:167], v[112:127]
	s_waitcnt lgkmcnt(2)
	v_mfma_f32_32x32x16_bf16 v[80:95], v[160:163], v[168:171], v[80:95]
	s_waitcnt lgkmcnt(1)
	v_mfma_f32_32x32x16_bf16 v[48:63], v[160:163], v[172:175], v[48:63]
	s_waitcnt lgkmcnt(0)
	v_mfma_f32_32x32x16_bf16 v[16:31], v[160:163], v[176:179], v[16:31]
	ds_read_b128 v[160:163], v214 offset:41472
	s_waitcnt lgkmcnt(0)
	v_mfma_f32_32x32x16_bf16 v[96:111], v[160:163], v[164:167], v[96:111]
	v_mfma_f32_32x32x16_bf16 v[64:79], v[160:163], v[168:171], v[64:79]
	v_mfma_f32_32x32x16_bf16 v[32:47], v[160:163], v[172:175], v[32:47]
	ds_read_b128 v[164:167], v214 offset:36896
	ds_read_b128 v[168:171], v215 offset:32
	ds_read_b128 v[172:175], v215 offset:4640
	ds_read_b128 v[180:183], v215 offset:9248
	ds_read_b128 v[196:199], v215 offset:13856
	ds_read_b128 v[202:205], v214 offset:41504
	v_mfma_f32_32x32x16_bf16 v[0:15], v[160:163], v[176:179], v[0:15]
	s_and_b32 s12, s35, 2
	s_mul_i32 s12, s12, 0x9000
	v_add_u32_e32 v216, s12, v193
	s_waitcnt vmcnt(7)
	ds_write_b128 v216, v[128:131]
	s_waitcnt vmcnt(6)
	ds_write_b128 v216, v[132:135] offset:36864
	s_waitcnt vmcnt(5)
	ds_write_b128 v216, v[136:139] offset:9216
	s_waitcnt vmcnt(4)
	ds_write_b128 v216, v[140:143] offset:46080
	s_waitcnt vmcnt(3)
	ds_write_b128 v216, v[144:147] offset:18432
	s_waitcnt vmcnt(2)
	ds_write_b128 v216, v[148:151] offset:55296
	s_waitcnt vmcnt(1)
	ds_write_b128 v216, v[152:155] offset:27648
	s_waitcnt vmcnt(0)
	ds_write_b128 v216, v[156:159] offset:64512
	s_cmpk_gt_i32 s2, 0x680
	s_cbranch_scc1 .Lnl_1
	s_add_u32 s96, s92, s2
	s_addc_u32 s97, s93, s3
	s_add_u32 s98, s94, s2
	s_addc_u32 s99, s95, s3
	global_load_dwordx4 v[128:131], v248, s[96:97] offset:256
	global_load_dwordx4 v[132:135], v248, s[98:99] offset:256
	global_load_dwordx4 v[136:139], v249, s[96:97] offset:256
	global_load_dwordx4 v[140:143], v249, s[98:99] offset:256
	global_load_dwordx4 v[144:147], v250, s[96:97] offset:256
	global_load_dwordx4 v[148:151], v250, s[98:99] offset:256
	global_load_dwordx4 v[152:155], v251, s[96:97] offset:256
	global_load_dwordx4 v[156:159], v251, s[98:99] offset:256
.Lnl_1:
	s_waitcnt lgkmcnt(12)
	v_mfma_f32_32x32x16_bf16 v[112:127], v[164:167], v[168:171], v[112:127]
	s_waitcnt lgkmcnt(11)
	v_mfma_f32_32x32x16_bf16 v[80:95], v[164:167], v[172:175], v[80:95]
	s_waitcnt lgkmcnt(10)
	v_mfma_f32_32x32x16_bf16 v[48:63], v[164:167], v[180:183], v[48:63]
	s_waitcnt lgkmcnt(9)
	v_mfma_f32_32x32x16_bf16 v[16:31], v[164:167], v[196:199], v[16:31]
	s_waitcnt lgkmcnt(8)
	v_mfma_f32_32x32x16_bf16 v[96:111], v[202:205], v[168:171], v[96:111]
	v_mfma_f32_32x32x16_bf16 v[64:79], v[202:205], v[172:175], v[64:79]
	ds_read_b128 v[160:163], v214 offset:36928
	ds_read_b128 v[206:209], v214 offset:41536
	ds_read_b128 v[164:167], v215 offset:64
	ds_read_b128 v[168:171], v215 offset:4672
	ds_read_b128 v[172:175], v215 offset:9280
	ds_read_b128 v[210:213], v215 offset:13888
	v_mfma_f32_32x32x16_bf16 v[32:47], v[202:205], v[180:183], v[32:47]
	v_mfma_f32_32x32x16_bf16 v[0:15], v[202:205], v[196:199], v[0:15]
	s_waitcnt lgkmcnt(3)
	v_mfma_f32_32x32x16_bf16 v[112:127], v[160:163], v[164:167], v[112:127]
	s_waitcnt lgkmcnt(2)
	v_mfma_f32_32x32x16_bf16 v[80:95], v[160:163], v[168:171], v[80:95]
	s_waitcnt lgkmcnt(1)
	v_mfma_f32_32x32x16_bf16 v[48:63], v[160:163], v[172:175], v[48:63]
	s_waitcnt lgkmcnt(0)
	v_mfma_f32_32x32x16_bf16 v[16:31], v[160:163], v[210:213], v[16:31]
	v_mfma_f32_32x32x16_bf16 v[96:111], v[206:209], v[164:167], v[96:111]
	v_mfma_f32_32x32x16_bf16 v[64:79], v[206:209], v[168:171], v[64:79]
	v_mfma_f32_32x32x16_bf16 v[32:47], v[206:209], v[172:175], v[32:47]
	ds_read_b128 v[176:179], v214 offset:36960
	ds_read_b128 v[160:163], v214 offset:41568
	ds_read_b128 v[180:183], v215 offset:96
	ds_read_b128 v[172:175], v215 offset:4704
	ds_read_b128 v[168:171], v215 offset:9312
	ds_read_b128 v[164:167], v215 offset:13920
	v_mfma_f32_32x32x16_bf16 v[0:15], v[206:209], v[210:213], v[0:15]
	s_branch .LBB0_215

.LBB0_448:
	s_add_i32 s12, s36, -2
	s_and_b32 s12, s12, 2
	s_mul_i32 s12, s12, 0x9000
	s_add_i32 s12, s12, 0
	v_add3_u32 v193, s12, v192, v188
	ds_read_b128 v[160:163], v193
	ds_read_b128 v[168:171], v193 offset:4608
	ds_read_b128 v[172:175], v193 offset:9216
	ds_read_b128 v[176:179], v193 offset:13824
	v_add3_u32 v197, s12, v191, v188
	ds_read_b128 v[164:167], v197 offset:36864
	s_cmpk_eq_i32 s2, 0x780
	s_waitcnt lgkmcnt(0)
	v_mfma_f32_32x32x16_bf16 v[32:47], v[160:163], v[164:167], v[32:47]
	v_mfma_f32_32x32x16_bf16 v[64:79], v[168:171], v[164:167], v[64:79]
	v_mfma_f32_32x32x16_bf16 v[96:111], v[172:175], v[164:167], v[96:111]
	v_mfma_f32_32x32x16_bf16 v[112:127], v[176:179], v[164:167], v[112:127]
	ds_read_b128 v[164:167], v197 offset:41472
	s_waitcnt lgkmcnt(0)
	v_mfma_f32_32x32x16_bf16 v[0:15], v[160:163], v[164:167], v[0:15]
	v_mfma_f32_32x32x16_bf16 v[16:31], v[168:171], v[164:167], v[16:31]
	v_mfma_f32_32x32x16_bf16 v[48:63], v[172:175], v[164:167], v[48:63]
	ds_read_b128 v[160:163], v197 offset:36896
	ds_read_b128 v[168:171], v193 offset:32
	ds_read_b128 v[172:175], v193 offset:4640
	ds_read_b128 v[180:183], v193 offset:9248
	ds_read_b128 v[202:205], v193 offset:13856
	ds_read_b128 v[206:209], v197 offset:41504
	v_mfma_f32_32x32x16_bf16 v[80:95], v[176:179], v[164:167], v[80:95]
	s_and_b32 s12, s36, 2
	s_mul_i32 s12, s12, 0x9000
	v_add_u32_e32 v198, s12, v190
	s_waitcnt vmcnt(7)
	ds_write_b128 v198, v[128:131]
	s_waitcnt vmcnt(6)
	ds_write_b128 v198, v[132:135] offset:36864
	s_waitcnt vmcnt(5)
	ds_write_b128 v198, v[136:139] offset:9216
	s_waitcnt vmcnt(4)
	ds_write_b128 v198, v[140:143] offset:46080
	s_waitcnt vmcnt(3)
	ds_write_b128 v198, v[144:147] offset:18432
	s_waitcnt vmcnt(2)
	ds_write_b128 v198, v[148:151] offset:55296
	s_waitcnt vmcnt(1)
	ds_write_b128 v198, v[152:155] offset:27648
	s_waitcnt vmcnt(0)
	ds_write_b128 v198, v[156:159] offset:64512
	s_cmpk_gt_i32 s2, 0x680
	s_cbranch_scc1 .Lnl_2
	s_add_u32 s96, s92, s2
	s_addc_u32 s97, s93, s3
	s_add_u32 s98, s94, s2
	s_addc_u32 s99, s95, s3
	global_load_dwordx4 v[128:131], v248, s[96:97] offset:256
	global_load_dwordx4 v[132:135], v248, s[98:99] offset:256
	global_load_dwordx4 v[136:139], v249, s[96:97] offset:256
	global_load_dwordx4 v[140:143], v249, s[98:99] offset:256
	global_load_dwordx4 v[144:147], v250, s[96:97] offset:256
	global_load_dwordx4 v[148:151], v250, s[98:99] offset:256
	global_load_dwordx4 v[152:155], v251, s[96:97] offset:256
	global_load_dwordx4 v[156:159], v251, s[98:99] offset:256
.Lnl_2:
	s_waitcnt lgkmcnt(12)
	v_mfma_f32_32x32x16_bf16 v[32:47], v[168:171], v[160:163], v[32:47]
	s_waitcnt lgkmcnt(11)
	v_mfma_f32_32x32x16_bf16 v[64:79], v[172:175], v[160:163], v[64:79]
	s_waitcnt lgkmcnt(10)
	v_mfma_f32_32x32x16_bf16 v[96:111], v[180:183], v[160:163], v[96:111]
	s_waitcnt lgkmcnt(9)
	v_mfma_f32_32x32x16_bf16 v[112:127], v[202:205], v[160:163], v[112:127]
	s_waitcnt lgkmcnt(8)
	v_mfma_f32_32x32x16_bf16 v[0:15], v[168:171], v[206:209], v[0:15]
	v_mfma_f32_32x32x16_bf16 v[16:31], v[172:175], v[206:209], v[16:31]
	ds_read_b128 v[160:163], v197 offset:36928
	ds_read_b128 v[210:213], v197 offset:41536
	ds_read_b128 v[164:167], v193 offset:64
	ds_read_b128 v[168:171], v193 offset:4672
	ds_read_b128 v[172:175], v193 offset:9280
	ds_read_b128 v[214:217], v193 offset:13888
	v_mfma_f32_32x32x16_bf16 v[48:63], v[180:183], v[206:209], v[48:63]
	v_mfma_f32_32x32x16_bf16 v[80:95], v[202:205], v[206:209], v[80:95]
	s_waitcnt lgkmcnt(3)
	v_mfma_f32_32x32x16_bf16 v[32:47], v[164:167], v[160:163], v[32:47]
	s_waitcnt lgkmcnt(2)
	v_mfma_f32_32x32x16_bf16 v[64:79], v[168:171], v[160:163], v[64:79]
	s_waitcnt lgkmcnt(1)
	v_mfma_f32_32x32x16_bf16 v[96:111], v[172:175], v[160:163], v[96:111]
	s_waitcnt lgkmcnt(0)
	v_mfma_f32_32x32x16_bf16 v[112:127], v[214:217], v[160:163], v[112:127]
	v_mfma_f32_32x32x16_bf16 v[0:15], v[164:167], v[210:213], v[0:15]
	v_mfma_f32_32x32x16_bf16 v[16:31], v[168:171], v[210:213], v[16:31]
	v_mfma_f32_32x32x16_bf16 v[48:63], v[172:175], v[210:213], v[48:63]
	ds_read_b128 v[176:179], v197 offset:36960
	ds_read_b128 v[160:163], v197 offset:41568
	ds_read_b128 v[180:183], v193 offset:96
	ds_read_b128 v[172:175], v193 offset:4704
	ds_read_b128 v[168:171], v193 offset:9312
	ds_read_b128 v[164:167], v193 offset:13920
	v_mfma_f32_32x32x16_bf16 v[80:95], v[214:217], v[210:213], v[80:95]
	s_branch .LBB0_447

.LBB0_460:
	s_add_i32 s12, s5, -2
	s_and_b32 s12, s12, 2
	s_mul_i32 s12, s12, 0x9000
	s_add_i32 s12, s12, 0
	v_add3_u32 v195, s12, v192, v194
	ds_read_b128 v[160:163], v195 offset:36864
	v_add3_u32 v200, s12, v193, v194
	ds_read_b128 v[164:167], v200
	ds_read_b128 v[168:171], v200 offset:4608
	ds_read_b128 v[172:175], v200 offset:9216
	ds_read_b128 v[176:179], v200 offset:13824
	s_cmpk_eq_i32 s2, 0x780
	s_waitcnt lgkmcnt(3)
	v_mfma_f32_32x32x16_bf16 v[112:127], v[160:163], v[164:167], v[112:127]
	s_waitcnt lgkmcnt(2)
	v_mfma_f32_32x32x16_bf16 v[96:111], v[160:163], v[168:171], v[96:111]
	s_waitcnt lgkmcnt(1)
	v_mfma_f32_32x32x16_bf16 v[80:95], v[160:163], v[172:175], v[80:95]
	s_waitcnt lgkmcnt(0)
	v_mfma_f32_32x32x16_bf16 v[48:63], v[160:163], v[176:179], v[48:63]
	ds_read_b128 v[160:163], v195 offset:41472
	s_waitcnt lgkmcnt(0)
	v_mfma_f32_32x32x16_bf16 v[64:79], v[160:163], v[164:167], v[64:79]
	v_mfma_f32_32x32x16_bf16 v[32:47], v[160:163], v[168:171], v[32:47]
	v_mfma_f32_32x32x16_bf16 v[16:31], v[160:163], v[172:175], v[16:31]
	ds_read_b128 v[164:167], v195 offset:36896
	ds_read_b128 v[168:171], v200 offset:32
	ds_read_b128 v[172:175], v200 offset:4640
	ds_read_b128 v[180:183], v200 offset:9248
	ds_read_b128 v[196:199], v200 offset:13856
	ds_read_b128 v[202:205], v195 offset:41504
	v_mfma_f32_32x32x16_bf16 v[0:15], v[160:163], v[176:179], v[0:15]
	s_and_b32 s12, s5, 2
	s_mul_i32 s12, s12, 0x9000
	v_add_u32_e32 v206, s12, v185
	s_waitcnt vmcnt(7)
	ds_write_b128 v206, v[128:131]
	s_waitcnt vmcnt(6)
	ds_write_b128 v206, v[132:135] offset:36864
	s_waitcnt vmcnt(5)
	ds_write_b128 v206, v[136:139] offset:9216
	s_waitcnt vmcnt(4)
	ds_write_b128 v206, v[140:143] offset:46080
	s_waitcnt vmcnt(3)
	ds_write_b128 v206, v[144:147] offset:18432
	s_waitcnt vmcnt(2)
	ds_write_b128 v206, v[148:151] offset:55296
	s_waitcnt vmcnt(1)
	ds_write_b128 v206, v[152:155] offset:27648
	s_waitcnt vmcnt(0)
	ds_write_b128 v206, v[156:159] offset:64512
	s_cmpk_gt_i32 s2, 0x680
	s_cbranch_scc1 .Lnl_3
	s_add_u32 s96, s92, s2
	s_addc_u32 s97, s93, s3
	s_add_u32 s98, s94, s2
	s_addc_u32 s99, s95, s3
	global_load_dwordx4 v[128:131], v248, s[96:97] offset:256
	global_load_dwordx4 v[132:135], v248, s[98:99] offset:256
	global_load_dwordx4 v[136:139], v249, s[96:97] offset:256
	global_load_dwordx4 v[140:143], v249, s[98:99] offset:256
	global_load_dwordx4 v[144:147], v250, s[96:97] offset:256
	global_load_dwordx4 v[148:151], v250, s[98:99] offset:256
	global_load_dwordx4 v[152:155], v251, s[96:97] offset:256
	global_load_dwordx4 v[156:159], v251, s[98:99] offset:256
.Lnl_3:
	s_waitcnt lgkmcnt(12)
	v_mfma_f32_32x32x16_bf16 v[112:127], v[164:167], v[168:171], v[112:127]
	s_waitcnt lgkmcnt(11)
	v_mfma_f32_32x32x16_bf16 v[96:111], v[164:167], v[172:175], v[96:111]
	s_waitcnt lgkmcnt(10)
	v_mfma_f32_32x32x16_bf16 v[80:95], v[164:167], v[180:183], v[80:95]
	s_waitcnt lgkmcnt(9)
	v_mfma_f32_32x32x16_bf16 v[48:63], v[164:167], v[196:199], v[48:63]
	s_waitcnt lgkmcnt(8)
	v_mfma_f32_32x32x16_bf16 v[64:79], v[202:205], v[168:171], v[64:79]
	v_mfma_f32_32x32x16_bf16 v[32:47], v[202:205], v[172:175], v[32:47]
	ds_read_b128 v[160:163], v195 offset:36928
	ds_read_b128 v[210:213], v195 offset:41536
	ds_read_b128 v[164:167], v200 offset:64
	ds_read_b128 v[168:171], v200 offset:4672
	ds_read_b128 v[172:175], v200 offset:9280
	ds_read_b128 v[216:219], v200 offset:13888
	v_mfma_f32_32x32x16_bf16 v[16:31], v[202:205], v[180:183], v[16:31]
	v_mfma_f32_32x32x16_bf16 v[0:15], v[202:205], v[196:199], v[0:15]
	s_waitcnt lgkmcnt(3)
	v_mfma_f32_32x32x16_bf16 v[112:127], v[160:163], v[164:167], v[112:127]
	s_waitcnt lgkmcnt(2)
	v_mfma_f32_32x32x16_bf16 v[96:111], v[160:163], v[168:171], v[96:111]
	s_waitcnt lgkmcnt(1)
	v_mfma_f32_32x32x16_bf16 v[80:95], v[160:163], v[172:175], v[80:95]
	s_waitcnt lgkmcnt(0)
	v_mfma_f32_32x32x16_bf16 v[48:63], v[160:163], v[216:219], v[48:63]
	v_mfma_f32_32x32x16_bf16 v[64:79], v[210:213], v[164:167], v[64:79]
	v_mfma_f32_32x32x16_bf16 v[32:47], v[210:213], v[168:171], v[32:47]
	v_mfma_f32_32x32x16_bf16 v[16:31], v[210:213], v[172:175], v[16:31]
	ds_read_b128 v[176:179], v195 offset:36960
	ds_read_b128 v[160:163], v195 offset:41568
	ds_read_b128 v[180:183], v200 offset:96
	ds_read_b128 v[172:175], v200 offset:4704
	ds_read_b128 v[168:171], v200 offset:9312
	ds_read_b128 v[164:167], v200 offset:13920
	v_mfma_f32_32x32x16_bf16 v[0:15], v[210:213], v[216:219], v[0:15]
	s_branch .LBB0_459

.LBB0_640:
	s_and_b32 s12, s38, 2
	s_mul_i32 s12, s12, 0x9000
	s_add_i32 s12, s12, 0
	v_add3_u32 v197, s12, v196, v195
	ds_read_b128 v[160:163], v197 offset:36864
	v_add3_u32 v198, s12, v194, v195
	ds_read_b128 v[164:167], v198
	ds_read_b128 v[168:171], v198 offset:4608
	ds_read_b128 v[172:175], v198 offset:9216
	ds_read_b128 v[176:179], v198 offset:13824
	s_cmp_lt_u32 s41, 15
	s_waitcnt lgkmcnt(3)
	v_mfma_f32_32x32x16_bf16 v[112:127], v[160:163], v[164:167], v[112:127]
	s_waitcnt lgkmcnt(2)
	v_mfma_f32_32x32x16_bf16 v[80:95], v[160:163], v[168:171], v[80:95]
	s_waitcnt lgkmcnt(1)
	v_mfma_f32_32x32x16_bf16 v[48:63], v[160:163], v[172:175], v[48:63]
	s_waitcnt lgkmcnt(0)
	v_mfma_f32_32x32x16_bf16 v[16:31], v[160:163], v[176:179], v[16:31]
	ds_read_b128 v[160:163], v197 offset:41472
	s_waitcnt lgkmcnt(0)
	v_mfma_f32_32x32x16_bf16 v[96:111], v[160:163], v[164:167], v[96:111]
	v_mfma_f32_32x32x16_bf16 v[64:79], v[160:163], v[168:171], v[64:79]
	v_mfma_f32_32x32x16_bf16 v[32:47], v[160:163], v[172:175], v[32:47]
	ds_read_b128 v[164:167], v197 offset:36896
	ds_read_b128 v[168:171], v198 offset:32
	ds_read_b128 v[172:175], v198 offset:4640
	ds_read_b128 v[180:183], v198 offset:9248
	ds_read_b128 v[202:205], v198 offset:13856
	ds_read_b128 v[206:209], v197 offset:41504
	v_mfma_f32_32x32x16_bf16 v[0:15], v[160:163], v[176:179], v[0:15]
	s_add_i32 s38, s38, 2
	s_and_b32 s12, s38, 2
	s_mul_i32 s12, s12, 0x9000
	v_add_u32_e32 v199, s12, v193
	s_waitcnt vmcnt(0)
	ds_write_b128 v199, v[128:131]
	ds_write_b128 v199, v[132:135] offset:36864
	ds_write_b128 v199, v[136:139] offset:9216
	ds_write_b128 v199, v[140:143] offset:46080
	ds_write_b128 v199, v[144:147] offset:18432
	ds_write_b128 v199, v[148:151] offset:55296
	ds_write_b128 v199, v[152:155] offset:27648
	ds_write_b128 v199, v[156:159] offset:64512
	s_cmpk_gt_i32 s2, 0x680
	s_cbranch_scc1 .Lnl_7
	s_add_u32 s96, s92, s2
	s_addc_u32 s97, s93, s3
	s_add_u32 s98, s94, s2
	s_addc_u32 s99, s95, s3
	global_load_dwordx4 v[128:131], v248, s[96:97] offset:256
	global_load_dwordx4 v[132:135], v248, s[98:99] offset:256
	global_load_dwordx4 v[136:139], v249, s[96:97] offset:256
	global_load_dwordx4 v[140:143], v249, s[98:99] offset:256
	global_load_dwordx4 v[144:147], v250, s[96:97] offset:256
	global_load_dwordx4 v[148:151], v250, s[98:99] offset:256
	global_load_dwordx4 v[152:155], v251, s[96:97] offset:256
	global_load_dwordx4 v[156:159], v251, s[98:99] offset:256
.Lnl_7:
	s_waitcnt lgkmcnt(12)
	v_mfma_f32_32x32x16_bf16 v[112:127], v[164:167], v[168:171], v[112:127]
	s_waitcnt lgkmcnt(11)
	v_mfma_f32_32x32x16_bf16 v[80:95], v[164:167], v[172:175], v[80:95]
	s_waitcnt lgkmcnt(10)
	v_mfma_f32_32x32x16_bf16 v[48:63], v[164:167], v[180:183], v[48:63]
	s_waitcnt lgkmcnt(9)
	v_mfma_f32_32x32x16_bf16 v[16:31], v[164:167], v[202:205], v[16:31]
	s_waitcnt lgkmcnt(8)
	v_mfma_f32_32x32x16_bf16 v[96:111], v[206:209], v[168:171], v[96:111]
	v_mfma_f32_32x32x16_bf16 v[64:79], v[206:209], v[172:175], v[64:79]
	ds_read_b128 v[160:163], v197 offset:36928
	ds_read_b128 v[210:213], v197 offset:41536
	ds_read_b128 v[164:167], v198 offset:64
	ds_read_b128 v[168:171], v198 offset:4672
	ds_read_b128 v[172:175], v198 offset:9280
	ds_read_b128 v[214:217], v198 offset:13888
	v_mfma_f32_32x32x16_bf16 v[32:47], v[206:209], v[180:183], v[32:47]
	v_mfma_f32_32x32x16_bf16 v[0:15], v[206:209], v[202:205], v[0:15]
	s_waitcnt lgkmcnt(3)
	v_mfma_f32_32x32x16_bf16 v[112:127], v[160:163], v[164:167], v[112:127]
	s_waitcnt lgkmcnt(2)
	v_mfma_f32_32x32x16_bf16 v[80:95], v[160:163], v[168:171], v[80:95]
	s_waitcnt lgkmcnt(1)
	v_mfma_f32_32x32x16_bf16 v[48:63], v[160:163], v[172:175], v[48:63]
	s_waitcnt lgkmcnt(0)
	v_mfma_f32_32x32x16_bf16 v[16:31], v[160:163], v[214:217], v[16:31]
	v_mfma_f32_32x32x16_bf16 v[96:111], v[210:213], v[164:167], v[96:111]
	v_mfma_f32_32x32x16_bf16 v[64:79], v[210:213], v[168:171], v[64:79]
	v_mfma_f32_32x32x16_bf16 v[32:47], v[210:213], v[172:175], v[32:47]
	ds_read_b128 v[176:179], v197 offset:36960
	ds_read_b128 v[160:163], v197 offset:41568
	ds_read_b128 v[180:183], v198 offset:96
	ds_read_b128 v[172:175], v198 offset:4704
	ds_read_b128 v[168:171], v198 offset:9312
	ds_read_b128 v[164:167], v198 offset:13920
	v_mfma_f32_32x32x16_bf16 v[0:15], v[210:213], v[214:217], v[0:15]
	s_branch .LBB0_639

.LBB0_758:
	s_add_i32 s12, s16, -2
	s_and_b32 s12, s12, 2
	s_mul_i32 s12, s12, 0x9000
	s_add_i32 s12, s12, 0
	v_add3_u32 v200, s12, v199, v198
	ds_read_b128 v[160:163], v200 offset:36864
	v_add3_u32 v218, s12, v185, v198
	ds_read_b128 v[164:167], v218
	ds_read_b128 v[168:171], v218 offset:4608
	ds_read_b128 v[172:175], v218 offset:9216
	ds_read_b128 v[176:179], v218 offset:13824
	s_cmpk_eq_i32 s4, 0x780
	s_waitcnt lgkmcnt(3)
	v_mfma_f32_32x32x16_bf16 v[112:127], v[160:163], v[164:167], v[112:127]
	s_waitcnt lgkmcnt(2)
	v_mfma_f32_32x32x16_bf16 v[96:111], v[160:163], v[168:171], v[96:111]
	s_waitcnt lgkmcnt(1)
	v_mfma_f32_32x32x16_bf16 v[80:95], v[160:163], v[172:175], v[80:95]
	s_waitcnt lgkmcnt(0)
	v_mfma_f32_32x32x16_bf16 v[48:63], v[160:163], v[176:179], v[48:63]
	ds_read_b128 v[160:163], v200 offset:41472
	s_waitcnt lgkmcnt(0)
	v_mfma_f32_32x32x16_bf16 v[64:79], v[160:163], v[164:167], v[64:79]
	v_mfma_f32_32x32x16_bf16 v[32:47], v[160:163], v[168:171], v[32:47]
	v_mfma_f32_32x32x16_bf16 v[16:31], v[160:163], v[172:175], v[16:31]
	ds_read_b128 v[164:167], v200 offset:36896
	ds_read_b128 v[168:171], v218 offset:32
	ds_read_b128 v[172:175], v218 offset:4640
	ds_read_b128 v[180:183], v218 offset:9248
	ds_read_b128 v[202:205], v218 offset:13856
	ds_read_b128 v[206:209], v200 offset:41504
	v_mfma_f32_32x32x16_bf16 v[0:15], v[160:163], v[176:179], v[0:15]
	s_and_b32 s12, s16, 2
	s_mul_i32 s12, s12, 0x9000
	s_add_i32 s12, s12, 0
	v_add_u32_e32 v220, s12, v194
	v_add_u32_e32 v219, s12, v184
	s_waitcnt vmcnt(7)
	ds_write_b128 v220, v[128:131]
	s_waitcnt vmcnt(6)
	ds_write_b128 v219, v[132:135] offset:36864
	v_add_u32_e32 v220, s12, v195
	s_waitcnt vmcnt(5)
	ds_write_b128 v220, v[136:139]
	s_waitcnt vmcnt(4)
	ds_write_b128 v219, v[140:143] offset:46080
	v_add_u32_e32 v220, s12, v196
	s_waitcnt vmcnt(3)
	ds_write_b128 v220, v[144:147]
	s_waitcnt vmcnt(2)
	ds_write_b128 v219, v[148:151] offset:55296
	v_add_u32_e32 v220, s12, v197
	s_waitcnt vmcnt(1)
	ds_write_b128 v220, v[152:155]
	s_waitcnt vmcnt(0)
	ds_write_b128 v219, v[156:159] offset:64512
	s_cmpk_gt_i32 s4, 0x680
	s_cbranch_scc1 .Lnl_4
	s_add_u32 s96, s92, s4
	s_addc_u32 s97, s93, s5
	s_add_u32 s98, s94, s4
	s_addc_u32 s99, s95, s5
	global_load_dwordx4 v[128:131], v248, s[96:97] offset:256
	global_load_dwordx4 v[132:135], v248, s[98:99] offset:256
	global_load_dwordx4 v[136:139], v249, s[96:97] offset:256
	global_load_dwordx4 v[140:143], v249, s[98:99] offset:256
	global_load_dwordx4 v[144:147], v250, s[96:97] offset:256
	global_load_dwordx4 v[148:151], v250, s[98:99] offset:256
	global_load_dwordx4 v[152:155], v251, s[96:97] offset:256
	global_load_dwordx4 v[156:159], v251, s[98:99] offset:256
.Lnl_4:
	s_waitcnt lgkmcnt(12)
	v_mfma_f32_32x32x16_bf16 v[112:127], v[164:167], v[168:171], v[112:127]
	s_waitcnt lgkmcnt(11)
	v_mfma_f32_32x32x16_bf16 v[96:111], v[164:167], v[172:175], v[96:111]
	s_waitcnt lgkmcnt(10)
	v_mfma_f32_32x32x16_bf16 v[80:95], v[164:167], v[180:183], v[80:95]
	s_waitcnt lgkmcnt(9)
	v_mfma_f32_32x32x16_bf16 v[48:63], v[164:167], v[202:205], v[48:63]
	s_waitcnt lgkmcnt(8)
	v_mfma_f32_32x32x16_bf16 v[64:79], v[206:209], v[168:171], v[64:79]
	v_mfma_f32_32x32x16_bf16 v[32:47], v[206:209], v[172:175], v[32:47]
	ds_read_b128 v[160:163], v200 offset:36928
	ds_read_b128 v[210:213], v200 offset:41536
	ds_read_b128 v[164:167], v218 offset:64
	ds_read_b128 v[168:171], v218 offset:4672
	ds_read_b128 v[172:175], v218 offset:9280
	ds_read_b128 v[214:217], v218 offset:13888
	v_mfma_f32_32x32x16_bf16 v[16:31], v[206:209], v[180:183], v[16:31]
	v_mfma_f32_32x32x16_bf16 v[0:15], v[206:209], v[202:205], v[0:15]
	s_waitcnt lgkmcnt(3)
	v_mfma_f32_32x32x16_bf16 v[112:127], v[160:163], v[164:167], v[112:127]
	s_waitcnt lgkmcnt(2)
	v_mfma_f32_32x32x16_bf16 v[96:111], v[160:163], v[168:171], v[96:111]
	s_waitcnt lgkmcnt(1)
	v_mfma_f32_32x32x16_bf16 v[80:95], v[160:163], v[172:175], v[80:95]
	s_waitcnt lgkmcnt(0)
	v_mfma_f32_32x32x16_bf16 v[48:63], v[160:163], v[214:217], v[48:63]
	v_mfma_f32_32x32x16_bf16 v[64:79], v[210:213], v[164:167], v[64:79]
	v_mfma_f32_32x32x16_bf16 v[32:47], v[210:213], v[168:171], v[32:47]
	v_mfma_f32_32x32x16_bf16 v[16:31], v[210:213], v[172:175], v[16:31]
	ds_read_b128 v[176:179], v200 offset:36960
	ds_read_b128 v[160:163], v200 offset:41568
	ds_read_b128 v[180:183], v218 offset:96
	ds_read_b128 v[172:175], v218 offset:4704
	ds_read_b128 v[168:171], v218 offset:9312
	ds_read_b128 v[164:167], v218 offset:13920
	v_mfma_f32_32x32x16_bf16 v[0:15], v[210:213], v[214:217], v[0:15]
	s_branch .LBB0_757

.LBB0_799:
	s_add_i32 s12, s36, -2
	s_and_b32 s12, s12, 2
	s_mul_i32 s12, s12, 0x9000
	s_add_i32 s12, s12, 0
	v_add3_u32 v214, s12, v195, v194
	ds_read_b128 v[160:163], v214 offset:36864
	v_add3_u32 v215, s12, v193, v194
	ds_read_b128 v[164:167], v215
	ds_read_b128 v[168:171], v215 offset:4608
	ds_read_b128 v[172:175], v215 offset:9216
	ds_read_b128 v[176:179], v215 offset:13824
	s_cmpk_eq_i32 s4, 0x180
	s_waitcnt lgkmcnt(3)
	v_mfma_f32_32x32x16_bf16 v[112:127], v[160:163], v[164:167], v[112:127]
	s_waitcnt lgkmcnt(2)
	v_mfma_f32_32x32x16_bf16 v[96:111], v[160:163], v[168:171], v[96:111]
	s_waitcnt lgkmcnt(1)
	v_mfma_f32_32x32x16_bf16 v[64:79], v[160:163], v[172:175], v[64:79]
	s_waitcnt lgkmcnt(0)
	v_mfma_f32_32x32x16_bf16 v[32:47], v[160:163], v[176:179], v[32:47]
	ds_read_b128 v[160:163], v214 offset:41472
	s_waitcnt lgkmcnt(0)
	v_mfma_f32_32x32x16_bf16 v[80:95], v[160:163], v[164:167], v[80:95]
	v_mfma_f32_32x32x16_bf16 v[48:63], v[160:163], v[168:171], v[48:63]
	v_mfma_f32_32x32x16_bf16 v[16:31], v[160:163], v[172:175], v[16:31]
	ds_read_b128 v[164:167], v214 offset:36896
	ds_read_b128 v[168:171], v215 offset:32
	ds_read_b128 v[172:175], v215 offset:4640
	ds_read_b128 v[180:183], v215 offset:9248
	ds_read_b128 v[196:199], v215 offset:13856
	ds_read_b128 v[202:205], v214 offset:41504
	v_mfma_f32_32x32x16_bf16 v[0:15], v[160:163], v[176:179], v[0:15]
	s_and_b32 s12, s36, 2
	s_mul_i32 s12, s12, 0x9000
	v_add_u32_e32 v216, s12, v192
	s_waitcnt vmcnt(7)
	ds_write_b128 v216, v[128:131]
	s_waitcnt vmcnt(6)
	ds_write_b128 v216, v[132:135] offset:36864
	s_waitcnt vmcnt(5)
	ds_write_b128 v216, v[136:139] offset:9216
	s_waitcnt vmcnt(4)
	ds_write_b128 v216, v[140:143] offset:46080
	s_waitcnt vmcnt(3)
	ds_write_b128 v216, v[144:147] offset:18432
	s_waitcnt vmcnt(2)
	ds_write_b128 v216, v[148:151] offset:55296
	s_waitcnt vmcnt(1)
	ds_write_b128 v216, v[152:155] offset:27648
	s_waitcnt vmcnt(0)
	ds_write_b128 v216, v[156:159] offset:64512
	s_cmpk_gt_i32 s4, 0x80
	s_cbranch_scc1 .Lnl_5
	s_add_u32 s96, s92, s4
	s_addc_u32 s97, s93, s5
	s_add_u32 s98, s94, s4
	s_addc_u32 s99, s95, s5
	global_load_dwordx4 v[128:131], v248, s[96:97] offset:256
	global_load_dwordx4 v[132:135], v248, s[98:99] offset:256
	global_load_dwordx4 v[136:139], v249, s[96:97] offset:256
	global_load_dwordx4 v[140:143], v249, s[98:99] offset:256
	global_load_dwordx4 v[144:147], v250, s[96:97] offset:256
	global_load_dwordx4 v[148:151], v250, s[98:99] offset:256
	global_load_dwordx4 v[152:155], v251, s[96:97] offset:256
	global_load_dwordx4 v[156:159], v251, s[98:99] offset:256
.Lnl_5:
	s_waitcnt lgkmcnt(12)
	v_mfma_f32_32x32x16_bf16 v[112:127], v[164:167], v[168:171], v[112:127]
	s_waitcnt lgkmcnt(11)
	v_mfma_f32_32x32x16_bf16 v[96:111], v[164:167], v[172:175], v[96:111]
	s_waitcnt lgkmcnt(10)
	v_mfma_f32_32x32x16_bf16 v[64:79], v[164:167], v[180:183], v[64:79]
	s_waitcnt lgkmcnt(9)
	v_mfma_f32_32x32x16_bf16 v[32:47], v[164:167], v[196:199], v[32:47]
	s_waitcnt lgkmcnt(8)
	v_mfma_f32_32x32x16_bf16 v[80:95], v[202:205], v[168:171], v[80:95]
	v_mfma_f32_32x32x16_bf16 v[48:63], v[202:205], v[172:175], v[48:63]
	ds_read_b128 v[160:163], v214 offset:36928
	ds_read_b128 v[206:209], v214 offset:41536
	ds_read_b128 v[164:167], v215 offset:64
	ds_read_b128 v[168:171], v215 offset:4672
	ds_read_b128 v[172:175], v215 offset:9280
	ds_read_b128 v[210:213], v215 offset:13888
	v_mfma_f32_32x32x16_bf16 v[16:31], v[202:205], v[180:183], v[16:31]
	v_mfma_f32_32x32x16_bf16 v[0:15], v[202:205], v[196:199], v[0:15]
	s_waitcnt lgkmcnt(3)
	v_mfma_f32_32x32x16_bf16 v[112:127], v[160:163], v[164:167], v[112:127]
	s_waitcnt lgkmcnt(2)
	v_mfma_f32_32x32x16_bf16 v[96:111], v[160:163], v[168:171], v[96:111]
	s_waitcnt lgkmcnt(1)
	v_mfma_f32_32x32x16_bf16 v[64:79], v[160:163], v[172:175], v[64:79]
	s_waitcnt lgkmcnt(0)
	v_mfma_f32_32x32x16_bf16 v[32:47], v[160:163], v[210:213], v[32:47]
	v_mfma_f32_32x32x16_bf16 v[80:95], v[206:209], v[164:167], v[80:95]
	v_mfma_f32_32x32x16_bf16 v[48:63], v[206:209], v[168:171], v[48:63]
	v_mfma_f32_32x32x16_bf16 v[16:31], v[206:209], v[172:175], v[16:31]
	ds_read_b128 v[176:179], v214 offset:36960
	ds_read_b128 v[160:163], v214 offset:41568
	ds_read_b128 v[180:183], v215 offset:96
	ds_read_b128 v[172:175], v215 offset:4704
	ds_read_b128 v[168:171], v215 offset:9312
	ds_read_b128 v[164:167], v215 offset:13920
	v_mfma_f32_32x32x16_bf16 v[0:15], v[206:209], v[210:213], v[0:15]
	s_branch .LBB0_798

.LBB0_958:
	s_and_b32 s6, s34, 2
	s_mul_i32 s6, s6, 0x9000
	s_add_i32 s6, s6, 0
	v_add3_u32 v214, s6, v195, v200
	ds_read_b128 v[160:163], v214 offset:36864
	v_add3_u32 v215, s6, v194, v200
	ds_read_b128 v[164:167], v215
	ds_read_b128 v[168:171], v215 offset:4608
	ds_read_b128 v[172:175], v215 offset:9216
	ds_read_b128 v[176:179], v215 offset:13824
	s_cmp_lt_u32 s39, 43
	s_waitcnt lgkmcnt(3)
	v_mfma_f32_32x32x16_bf16 v[112:127], v[160:163], v[164:167], v[112:127]
	s_waitcnt lgkmcnt(2)
	v_mfma_f32_32x32x16_bf16 v[80:95], v[160:163], v[168:171], v[80:95]
	s_waitcnt lgkmcnt(1)
	v_mfma_f32_32x32x16_bf16 v[48:63], v[160:163], v[172:175], v[48:63]
	s_waitcnt lgkmcnt(0)
	v_mfma_f32_32x32x16_bf16 v[16:31], v[160:163], v[176:179], v[16:31]
	ds_read_b128 v[160:163], v214 offset:41472
	s_waitcnt lgkmcnt(0)
	v_mfma_f32_32x32x16_bf16 v[96:111], v[160:163], v[164:167], v[96:111]
	v_mfma_f32_32x32x16_bf16 v[64:79], v[160:163], v[168:171], v[64:79]
	v_mfma_f32_32x32x16_bf16 v[32:47], v[160:163], v[172:175], v[32:47]
	ds_read_b128 v[164:167], v214 offset:36896
	ds_read_b128 v[168:171], v215 offset:32
	ds_read_b128 v[172:175], v215 offset:4640
	ds_read_b128 v[180:183], v215 offset:9248
	ds_read_b128 v[196:199], v215 offset:13856
	ds_read_b128 v[202:205], v214 offset:41504
	v_mfma_f32_32x32x16_bf16 v[0:15], v[160:163], v[176:179], v[0:15]
	s_add_i32 s34, s34, 2
	s_and_b32 s6, s34, 2
	s_mul_i32 s6, s6, 0x9000
	v_add_u32_e32 v216, s6, v193
	s_waitcnt vmcnt(0)
	ds_write_b128 v216, v[128:131]
	ds_write_b128 v216, v[132:135] offset:36864
	ds_write_b128 v216, v[136:139] offset:9216
	ds_write_b128 v216, v[140:143] offset:46080
	ds_write_b128 v216, v[144:147] offset:18432
	ds_write_b128 v216, v[148:151] offset:55296
	ds_write_b128 v216, v[152:155] offset:27648
	ds_write_b128 v216, v[156:159] offset:64512
	s_cmpk_gt_i32 s2, 0x1480
	s_cbranch_scc1 .Lnl_8
	s_add_u32 s96, s92, s2
	s_addc_u32 s97, s93, s3
	s_add_u32 s98, s94, s2
	s_addc_u32 s99, s95, s3
	global_load_dwordx4 v[128:131], v248, s[96:97] offset:256
	global_load_dwordx4 v[132:135], v248, s[98:99] offset:256
	global_load_dwordx4 v[136:139], v249, s[96:97] offset:256
	global_load_dwordx4 v[140:143], v249, s[98:99] offset:256
	global_load_dwordx4 v[144:147], v250, s[96:97] offset:256
	global_load_dwordx4 v[148:151], v250, s[98:99] offset:256
	global_load_dwordx4 v[152:155], v251, s[96:97] offset:256
	global_load_dwordx4 v[156:159], v251, s[98:99] offset:256

.LBB0_1049:
	s_add_i32 s12, s35, -2
	s_and_b32 s12, s12, 2
	s_mul_i32 s12, s12, 0x9000
	s_add_i32 s12, s12, 0
	v_add3_u32 v200, s12, v195, v191
	ds_read_b128 v[160:163], v200 offset:36864
	v_add3_u32 v214, s12, v190, v191
	ds_read_b128 v[164:167], v214
	ds_read_b128 v[168:171], v214 offset:4608
	ds_read_b128 v[172:175], v214 offset:9216
	ds_read_b128 v[176:179], v214 offset:13824
	s_cmpk_eq_i32 s2, 0x780
	s_waitcnt lgkmcnt(3)
	v_mfma_f32_32x32x16_bf16 v[112:127], v[160:163], v[164:167], v[112:127]
	s_waitcnt lgkmcnt(2)
	v_mfma_f32_32x32x16_bf16 v[80:95], v[160:163], v[168:171], v[80:95]
	s_waitcnt lgkmcnt(1)
	v_mfma_f32_32x32x16_bf16 v[48:63], v[160:163], v[172:175], v[48:63]
	s_waitcnt lgkmcnt(0)
	v_mfma_f32_32x32x16_bf16 v[16:31], v[160:163], v[176:179], v[16:31]
	ds_read_b128 v[160:163], v200 offset:41472
	s_waitcnt lgkmcnt(0)
	v_mfma_f32_32x32x16_bf16 v[96:111], v[160:163], v[164:167], v[96:111]
	v_mfma_f32_32x32x16_bf16 v[64:79], v[160:163], v[168:171], v[64:79]
	v_mfma_f32_32x32x16_bf16 v[32:47], v[160:163], v[172:175], v[32:47]
	ds_read_b128 v[164:167], v200 offset:36896
	ds_read_b128 v[168:171], v214 offset:32
	ds_read_b128 v[172:175], v214 offset:4640
	ds_read_b128 v[180:183], v214 offset:9248
	ds_read_b128 v[196:199], v214 offset:13856
	ds_read_b128 v[202:205], v200 offset:41504
	v_mfma_f32_32x32x16_bf16 v[0:15], v[160:163], v[176:179], v[0:15]
	s_and_b32 s12, s35, 2
	s_mul_i32 s12, s12, 0x9000
	v_add_u32_e32 v215, s12, v189
	s_waitcnt vmcnt(7)
	ds_write_b128 v215, v[128:131]
	s_waitcnt vmcnt(6)
	ds_write_b128 v215, v[132:135] offset:36864
	s_waitcnt vmcnt(5)
	ds_write_b128 v215, v[136:139] offset:9216
	s_waitcnt vmcnt(4)
	ds_write_b128 v215, v[140:143] offset:46080
	s_waitcnt vmcnt(3)
	ds_write_b128 v215, v[144:147] offset:18432
	s_waitcnt vmcnt(2)
	ds_write_b128 v215, v[148:151] offset:55296
	s_waitcnt vmcnt(1)
	ds_write_b128 v215, v[152:155] offset:27648
	s_waitcnt vmcnt(0)
	ds_write_b128 v215, v[156:159] offset:64512
	s_cmpk_gt_i32 s2, 0x680
	s_cbranch_scc1 .Lnl_6
	s_add_u32 s96, s92, s2
	s_addc_u32 s97, s93, s3
	s_add_u32 s98, s94, s2
	s_addc_u32 s99, s95, s3
	global_load_dwordx4 v[128:131], v248, s[96:97] offset:256
	global_load_dwordx4 v[132:135], v248, s[98:99] offset:256
	global_load_dwordx4 v[136:139], v249, s[96:97] offset:256
	global_load_dwordx4 v[140:143], v249, s[98:99] offset:256
	global_load_dwordx4 v[144:147], v250, s[96:97] offset:256
	global_load_dwordx4 v[148:151], v250, s[98:99] offset:256
	global_load_dwordx4 v[152:155], v251, s[96:97] offset:256
	global_load_dwordx4 v[156:159], v251, s[98:99] offset:256
.Lnl_6:
	s_waitcnt lgkmcnt(12)
	v_mfma_f32_32x32x16_bf16 v[112:127], v[164:167], v[168:171], v[112:127]
	s_waitcnt lgkmcnt(11)
	v_mfma_f32_32x32x16_bf16 v[80:95], v[164:167], v[172:175], v[80:95]
	s_waitcnt lgkmcnt(10)
	v_mfma_f32_32x32x16_bf16 v[48:63], v[164:167], v[180:183], v[48:63]
	s_waitcnt lgkmcnt(9)
	v_mfma_f32_32x32x16_bf16 v[16:31], v[164:167], v[196:199], v[16:31]
	s_waitcnt lgkmcnt(8)
	v_mfma_f32_32x32x16_bf16 v[96:111], v[202:205], v[168:171], v[96:111]
	v_mfma_f32_32x32x16_bf16 v[64:79], v[202:205], v[172:175], v[64:79]
	ds_read_b128 v[160:163], v200 offset:36928
	ds_read_b128 v[206:209], v200 offset:41536
	ds_read_b128 v[164:167], v214 offset:64
	ds_read_b128 v[168:171], v214 offset:4672
	ds_read_b128 v[172:175], v214 offset:9280
	ds_read_b128 v[210:213], v214 offset:13888
	v_mfma_f32_32x32x16_bf16 v[32:47], v[202:205], v[180:183], v[32:47]
	v_mfma_f32_32x32x16_bf16 v[0:15], v[202:205], v[196:199], v[0:15]
	s_waitcnt lgkmcnt(3)
	v_mfma_f32_32x32x16_bf16 v[112:127], v[160:163], v[164:167], v[112:127]
	s_waitcnt lgkmcnt(2)
	v_mfma_f32_32x32x16_bf16 v[80:95], v[160:163], v[168:171], v[80:95]
	s_waitcnt lgkmcnt(1)
	v_mfma_f32_32x32x16_bf16 v[48:63], v[160:163], v[172:175], v[48:63]
	s_waitcnt lgkmcnt(0)
	v_mfma_f32_32x32x16_bf16 v[16:31], v[160:163], v[210:213], v[16:31]
	v_mfma_f32_32x32x16_bf16 v[96:111], v[206:209], v[164:167], v[96:111]
	v_mfma_f32_32x32x16_bf16 v[64:79], v[206:209], v[168:171], v[64:79]
	v_mfma_f32_32x32x16_bf16 v[32:47], v[206:209], v[172:175], v[32:47]
	ds_read_b128 v[176:179], v200 offset:36960
	ds_read_b128 v[160:163], v200 offset:41568
	ds_read_b128 v[180:183], v214 offset:96
	ds_read_b128 v[172:175], v214 offset:4704
	ds_read_b128 v[168:171], v214 offset:9312
	ds_read_b128 v[164:167], v214 offset:13920
	v_mfma_f32_32x32x16_bf16 v[0:15], v[206:209], v[210:213], v[0:15]
	s_branch .LBB0_1048
